# phase B mono-key via ashr/or/xor (3 VALU), phase A bin select via v_max_i32
# baseline (speedup 1.0000x reference)
; #define IDX_PIPE_BEGIN() bf16x8 nk0[4], nk1[4]; IDX_LOAD(0, nk0, nk1);
; DI int score_bin(float s, float isg) {
;   const float a = fabsf(s) * isg;
;   const int e = (int)(__float_as_uint(a) >> 18) - ((130 << 5) - 256);
;   const int ec = (e + 192) >> 2;
;   int k = e >= 64 ? e : ec;
;   k = k < 0 ? 0 : (k > 254 ? 254 : k);
;   return (s > 0.f) ? (256 + k) : ((s < 0.f) ? (254 - k) : 255);
; DI void attn_item(const Params& P, unsigned char* smem, bool samp, int b, int c) {
;     ...
;     for (int i = lane; i < 2048; i += 64) hist[i] = 0u;
;     { IDX_PIPE_BEGIN();
; #pragma unroll 1
;     for (int kt = 0; kt < ntiles; ++kt) {
;       float sc[4][2];
;       IDX_PIPE_STEP(kt, sc);
;       if (kt * 64 + 64 <= nkeys) {
;         for (int hf = 0; hf < 2; ++hf)
;           for (int i = 0; i < 4; ++i) {
;             const int bn = score_bin(sc[i][hf], scl[i]);
;             atomicAdd(&hist[(g + 2 * i) * 256 + (bn >> 1)], 1u << (16 * (bn & 1)));
.LBB0_302:
	s_nop 9
	v_med3_f32 v139, v20, 0, v187
	v_med3_f32 v138, v24, 0, v187
	v_med3_f32 v21, v21, 0, v187
	v_med3_f32 v20, v25, 0, v187
	v_pk_mul_f32 v[24:25], v[120:121], v[138:139]
	v_med3_f32 v141, v22, 0, v187
	v_med3_f32 v140, v26, 0, v187
	v_pk_fma_f32 v[20:21], v[122:123], v[20:21], v[24:25]
	v_med3_f32 v23, v23, 0, v187
	v_pk_fma_f32 v[20:21], v[124:125], v[140:141], v[20:21]
	v_med3_f32 v22, v27, 0, v187
	v_pk_fma_f32 v[22:23], v[126:127], v[22:23], v[20:21]
	v_med3_f32 v21, v28, 0, v187
	v_med3_f32 v20, v32, 0, v187
	v_med3_f32 v25, v29, 0, v187
	v_med3_f32 v24, v33, 0, v187
	v_pk_mul_f32 v[20:21], v[128:129], v[20:21]
	v_med3_f32 v27, v30, 0, v187
	v_med3_f32 v26, v34, 0, v187
	v_pk_fma_f32 v[20:21], v[130:131], v[24:25], v[20:21]
	v_med3_f32 v29, v31, 0, v187
	v_pk_fma_f32 v[20:21], v[132:133], v[26:27], v[20:21]
	v_med3_f32 v28, v35, 0, v187
	s_cmp_gt_u32 s13, s1
	v_pk_fma_f32 v[20:21], v[134:135], v[28:29], v[20:21]
	s_cbranch_scc1 .LBB0_304
	v_and_b32_e32 v25, 0x7fffffff, v23
	v_and_b32_e32 v24, 0x7fffffff, v22
	v_pk_mul_f32 v[24:25], v[102:103], v[24:25]
	s_nop 0
	v_lshrrev_b32_e32 v26, 18, v25
	v_add_u32_e32 v27, 0xfffff0c0, v26
	v_add_u32_e32 v26, 0xfffff180, v26
	v_ashrrev_i32_e32 v26, 2, v26
	s_nop 0
	s_mov_b64 s[8:9], -1
	s_nop 0
	v_max_i32_e32 v25, v26, v27
	v_med3_i32 v25, v25, 0, v188
	v_or_b32_e32 v26, 0x100, v25
	v_sub_u32_e32 v25, 0xfe, v25
	v_cmp_gt_f32_e32 vcc, 0, v23
	s_nop 1
	v_cndmask_b32_e32 v25, v189, v25, vcc
	v_cmp_lt_f32_e32 vcc, 0, v23
	s_nop 1
	v_cndmask_b32_e32 v25, v25, v26, vcc
	v_lshlrev_b32_e32 v26, 1, v25
	v_and_b32_e32 v26, 0x3fc, v26
	v_lshlrev_b32_e32 v25, 4, v25
	v_add_u32_e32 v26, v136, v26
	v_lshlrev_b32_e64 v25, v25, 1
	ds_add_u32 v26, v25
	v_lshrrev_b32_e32 v25, 18, v24
	v_add_u32_e32 v26, 0xfffff0c0, v25
	v_add_u32_e32 v25, 0xfffff180, v25
	v_ashrrev_i32_e32 v25, 2, v25
	s_nop 0
	s_nop 1
	v_max_i32_e32 v24, v25, v26
	v_med3_i32 v24, v24, 0, v188
	v_or_b32_e32 v25, 0x100, v24
	v_sub_u32_e32 v24, 0xfe, v24
	v_cmp_gt_f32_e32 vcc, 0, v22
	s_nop 1
	v_cndmask_b32_e32 v24, v189, v24, vcc
	v_cmp_lt_f32_e32 vcc, 0, v22
	s_nop 1
	v_cndmask_b32_e32 v24, v24, v25, vcc
	v_lshlrev_b32_e32 v25, 1, v24
	v_and_b32_e32 v25, 0x3fc, v25
	v_lshlrev_b32_e32 v24, 4, v24
	v_add_u32_e32 v25, v136, v25
	v_lshlrev_b32_e64 v24, v24, 1
	ds_add_u32 v25, v24 offset:2048
	v_and_b32_e32 v25, 0x7fffffff, v21
	v_and_b32_e32 v24, 0x7fffffff, v20
	v_pk_mul_f32 v[24:25], v[106:107], v[24:25]
	s_nop 0
	v_lshrrev_b32_e32 v26, 18, v25
	v_add_u32_e32 v27, 0xfffff0c0, v26
	v_add_u32_e32 v26, 0xfffff180, v26
	v_ashrrev_i32_e32 v26, 2, v26
	s_nop 0
	s_nop 1
	v_max_i32_e32 v25, v26, v27
	v_med3_i32 v25, v25, 0, v188
	v_or_b32_e32 v26, 0x100, v25
	v_sub_u32_e32 v25, 0xfe, v25
	v_cmp_gt_f32_e32 vcc, 0, v21
	s_nop 1
	v_cndmask_b32_e32 v25, v189, v25, vcc
	v_cmp_lt_f32_e32 vcc, 0, v21
	s_nop 1
	v_cndmask_b32_e32 v25, v25, v26, vcc
	v_lshlrev_b32_e32 v26, 1, v25
	v_and_b32_e32 v26, 0x3fc, v26
	v_lshlrev_b32_e32 v25, 4, v25
	v_add_u32_e32 v26, v136, v26
	v_lshlrev_b32_e64 v25, v25, 1
	ds_add_u32 v26, v25 offset:4096
	v_lshrrev_b32_e32 v25, 18, v24
	v_add_u32_e32 v26, 0xfffff0c0, v25
	v_add_u32_e32 v25, 0xfffff180, v25
	v_ashrrev_i32_e32 v25, 2, v25
	s_nop 0
	s_nop 1
	v_max_i32_e32 v24, v25, v26
	v_med3_i32 v24, v24, 0, v188
	v_or_b32_e32 v25, 0x100, v24
	v_sub_u32_e32 v24, 0xfe, v24
	v_cmp_gt_f32_e32 vcc, 0, v20
	s_nop 1
	v_cndmask_b32_e32 v24, v189, v24, vcc
	v_cmp_lt_f32_e32 vcc, 0, v20
	s_nop 1
	v_cndmask_b32_e32 v24, v24, v25, vcc
	v_lshlrev_b32_e32 v25, 1, v24
	v_and_b32_e32 v25, 0x3fc, v25
	v_lshlrev_b32_e32 v24, 4, v24
	v_add_u32_e32 v25, v136, v25
	v_lshlrev_b32_e64 v24, v24, 1
	ds_add_u32 v25, v24 offset:6144
	s_cbranch_execz .LBB0_305
	s_branch .LBB0_308

; DI int score_bin(float s, float isg) {
;   const float a = fabsf(s) * isg;
;   const int e = (int)(__float_as_uint(a) >> 18) - ((130 << 5) - 256);
;   const int ec = (e + 192) >> 2;
;   int k = e >= 64 ? e : ec;
;   k = k < 0 ? 0 : (k > 254 ? 254 : k);
;   return (s > 0.f) ? (256 + k) : ((s < 0.f) ? (254 - k) : 255);
; DI void attn_item(const Params& P, unsigned char* smem, bool samp, int b, int c) {
;     ...
;       } else {
;         for (int hf = 0; hf < 2; ++hf) {
;           const bool valid = (kt * 64 + hf * 32 + l32) < nkeys;
;           for (int i = 0; i < 4; ++i)
;             if (valid) {
;               const int bn = score_bin(sc[i][hf], scl[i]);
;               atomicAdd(&hist[(g + 2 * i) * 256 + (bn >> 1)], 1u << (16 * (bn & 1)));
;             }
;         }
.LBB0_305:
	v_add_u32_e32 v24, s13, v195
	v_cmp_gt_u32_e32 vcc, s0, v24
	s_and_saveexec_b64 s[6:7], vcc
	s_cbranch_execz .LBB0_307
	v_and_b32_e32 v27, 0x7fffffff, v23
	v_and_b32_e32 v26, 0x7fffffff, v22
	v_pk_mul_f32 v[26:27], v[102:103], v[26:27]
	s_nop 0
	v_lshrrev_b32_e32 v25, 18, v27
	v_add_u32_e32 v28, 0xfffff0c0, v25
	v_add_u32_e32 v25, 0xfffff180, v25
	v_ashrrev_i32_e32 v25, 2, v25
	s_nop 0
	s_nop 1
	v_max_i32_e32 v25, v25, v28
	v_med3_i32 v25, v25, 0, v188
	v_or_b32_e32 v27, 0x100, v25
	v_sub_u32_e32 v25, 0xfe, v25
	v_cmp_gt_f32_e32 vcc, 0, v23
	s_nop 1
	v_cndmask_b32_e32 v25, v189, v25, vcc
	v_cmp_lt_f32_e32 vcc, 0, v23
	s_nop 1
	v_cndmask_b32_e32 v23, v25, v27, vcc
	v_lshlrev_b32_e32 v25, 1, v23
	v_and_b32_e32 v25, 0x3fc, v25
	v_lshlrev_b32_e32 v23, 4, v23
	v_add_u32_e32 v25, v136, v25
	v_lshlrev_b32_e64 v23, v23, 1
	ds_add_u32 v25, v23
	v_lshrrev_b32_e32 v23, 18, v26
	v_add_u32_e32 v25, 0xfffff0c0, v23
	v_add_u32_e32 v23, 0xfffff180, v23
	v_ashrrev_i32_e32 v23, 2, v23
	s_nop 0
	s_nop 1
	v_max_i32_e32 v23, v23, v25
	v_med3_i32 v23, v23, 0, v188
	v_or_b32_e32 v25, 0x100, v23
	v_sub_u32_e32 v23, 0xfe, v23
	v_cmp_gt_f32_e32 vcc, 0, v22
	s_nop 1
	v_cndmask_b32_e32 v23, v189, v23, vcc
	v_cmp_lt_f32_e32 vcc, 0, v22
	s_nop 1
	v_cndmask_b32_e32 v22, v23, v25, vcc
	v_lshlrev_b32_e32 v23, 1, v22
	v_and_b32_e32 v23, 0x3fc, v23
	v_lshlrev_b32_e32 v22, 4, v22
	v_add_u32_e32 v23, v136, v23
	v_lshlrev_b32_e64 v22, v22, 1
	ds_add_u32 v23, v22 offset:2048
	v_and_b32_e32 v23, 0x7fffffff, v21
	v_and_b32_e32 v22, 0x7fffffff, v20
	v_pk_mul_f32 v[22:23], v[106:107], v[22:23]
	s_nop 0
	v_lshrrev_b32_e32 v25, 18, v23
	v_add_u32_e32 v26, 0xfffff0c0, v25
	v_add_u32_e32 v25, 0xfffff180, v25
	v_ashrrev_i32_e32 v25, 2, v25
	s_nop 0
	s_nop 1
	v_max_i32_e32 v23, v25, v26
	v_med3_i32 v23, v23, 0, v188
	v_or_b32_e32 v25, 0x100, v23
	v_sub_u32_e32 v23, 0xfe, v23
	v_cmp_gt_f32_e32 vcc, 0, v21
	s_nop 1
	v_cndmask_b32_e32 v23, v189, v23, vcc
	v_cmp_lt_f32_e32 vcc, 0, v21
	s_nop 1
	v_cndmask_b32_e32 v21, v23, v25, vcc
	v_lshlrev_b32_e32 v23, 1, v21
	v_and_b32_e32 v23, 0x3fc, v23
	v_lshlrev_b32_e32 v21, 4, v21
	v_add_u32_e32 v23, v136, v23
	v_lshlrev_b32_e64 v21, v21, 1
	ds_add_u32 v23, v21 offset:4096
	v_lshrrev_b32_e32 v21, 18, v22
	v_add_u32_e32 v23, 0xfffff0c0, v21
	v_add_u32_e32 v21, 0xfffff180, v21
	v_ashrrev_i32_e32 v21, 2, v21
	s_nop 0
	s_nop 1
	v_max_i32_e32 v21, v21, v23
	v_med3_i32 v21, v21, 0, v188
	v_or_b32_e32 v22, 0x100, v21
	v_sub_u32_e32 v21, 0xfe, v21
	v_cmp_gt_f32_e32 vcc, 0, v20
	s_nop 1
	v_cndmask_b32_e32 v21, v189, v21, vcc
	v_cmp_lt_f32_e32 vcc, 0, v20
	s_nop 1
	v_cndmask_b32_e32 v20, v21, v22, vcc
	v_lshlrev_b32_e32 v21, 1, v20
	v_and_b32_e32 v21, 0x3fc, v21
	v_lshlrev_b32_e32 v20, 4, v20
	v_add_u32_e32 v21, v136, v21
	v_lshlrev_b32_e64 v20, v20, 1
	ds_add_u32 v21, v20 offset:6144

; #define IDX_PIPE_BEGIN() bf16x8 nk0[4], nk1[4]; IDX_LOAD(0, nk0, nk1);
; DI int score_bin(float s, float isg) {
;   const float a = fabsf(s) * isg;
;   const int e = (int)(__float_as_uint(a) >> 18) - ((130 << 5) - 256);
;   const int ec = (e + 192) >> 2;
;   int k = e >= 64 ? e : ec;
;   k = k < 0 ? 0 : (k > 254 ? 254 : k);
;   return (s > 0.f) ? (256 + k) : ((s < 0.f) ? (254 - k) : 255);
; DI void attn_item(const Params& P, unsigned char* smem, bool samp, int b, int c) {
;     ...
;     for (int i = lane; i < 2048; i += 64) hist[i] = 0u;
;     { IDX_PIPE_BEGIN();
; #pragma unroll 1
;     for (int kt = 0; kt < ntiles; ++kt) {
;       float sc[4][2];
;       IDX_PIPE_STEP(kt, sc);
;       if (kt * 64 + 64 <= nkeys) {
;         for (int hf = 0; hf < 2; ++hf)
;           for (int i = 0; i < 4; ++i) {
;             const int bn = score_bin(sc[i][hf], scl[i]);
;             atomicAdd(&hist[(g + 2 * i) * 256 + (bn >> 1)], 1u << (16 * (bn & 1)));
.LBB0_308:
	s_and_saveexec_b64 s[6:7], s[8:9]
	s_cbranch_execz .LBB0_299
	v_med3_f32 v21, v4, 0, v187
	v_med3_f32 v20, v8, 0, v187
	v_med3_f32 v5, v5, 0, v187
	v_med3_f32 v4, v9, 0, v187
	v_pk_mul_f32 v[8:9], v[120:121], v[20:21]
	v_med3_f32 v23, v6, 0, v187
	v_med3_f32 v22, v10, 0, v187
	v_pk_fma_f32 v[4:5], v[122:123], v[4:5], v[8:9]
	v_med3_f32 v7, v7, 0, v187
	v_pk_fma_f32 v[4:5], v[124:125], v[22:23], v[4:5]
	v_med3_f32 v6, v11, 0, v187
	v_pk_fma_f32 v[4:5], v[126:127], v[6:7], v[4:5]
	v_med3_f32 v7, v12, 0, v187
	v_med3_f32 v6, v16, 0, v187
	v_med3_f32 v9, v13, 0, v187
	v_med3_f32 v8, v17, 0, v187
	v_pk_mul_f32 v[6:7], v[128:129], v[6:7]
	v_med3_f32 v11, v14, 0, v187
	v_pk_fma_f32 v[6:7], v[130:131], v[8:9], v[6:7]
	v_and_b32_e32 v9, 0x7fffffff, v5
	v_and_b32_e32 v8, 0x7fffffff, v4
	v_med3_f32 v10, v18, 0, v187
	v_pk_mul_f32 v[8:9], v[102:103], v[8:9]
	v_pk_fma_f32 v[6:7], v[132:133], v[10:11], v[6:7]
	v_lshrrev_b32_e32 v10, 18, v9
	v_add_u32_e32 v11, 0xfffff0c0, v10
	v_add_u32_e32 v10, 0xfffff180, v10
	v_ashrrev_i32_e32 v10, 2, v10
	s_nop 0
	v_med3_f32 v13, v15, 0, v187
	v_med3_f32 v12, v19, 0, v187
	v_max_i32_e32 v9, v10, v11
	v_med3_i32 v9, v9, 0, v188
	v_or_b32_e32 v10, 0x100, v9
	v_sub_u32_e32 v9, 0xfe, v9
	v_cmp_gt_f32_e32 vcc, 0, v5
	v_pk_fma_f32 v[6:7], v[134:135], v[12:13], v[6:7]
	s_nop 0
	v_cndmask_b32_e32 v9, v189, v9, vcc
	v_cmp_lt_f32_e32 vcc, 0, v5
	s_nop 1
	v_cndmask_b32_e32 v5, v9, v10, vcc
	v_lshlrev_b32_e32 v9, 1, v5
	v_and_b32_e32 v9, 0x3fc, v9
	v_lshlrev_b32_e32 v5, 4, v5
	v_add_u32_e32 v9, v136, v9
	v_lshlrev_b32_e64 v5, v5, 1
	ds_add_u32 v9, v5
	v_lshrrev_b32_e32 v5, 18, v8
	v_add_u32_e32 v9, 0xfffff0c0, v5
	v_add_u32_e32 v5, 0xfffff180, v5
	v_ashrrev_i32_e32 v5, 2, v5
	s_nop 0
	s_nop 1
	v_max_i32_e32 v5, v5, v9
	v_med3_i32 v5, v5, 0, v188
	v_or_b32_e32 v8, 0x100, v5
	v_sub_u32_e32 v5, 0xfe, v5
	v_cmp_gt_f32_e32 vcc, 0, v4
	s_nop 1
	v_cndmask_b32_e32 v5, v189, v5, vcc
	v_cmp_lt_f32_e32 vcc, 0, v4
	s_nop 1
	v_cndmask_b32_e32 v4, v5, v8, vcc
	v_lshlrev_b32_e32 v5, 1, v4
	v_and_b32_e32 v5, 0x3fc, v5
	v_lshlrev_b32_e32 v4, 4, v4
	v_add_u32_e32 v5, v136, v5
	v_lshlrev_b32_e64 v4, v4, 1
	ds_add_u32 v5, v4 offset:2048
	v_and_b32_e32 v5, 0x7fffffff, v7
	v_and_b32_e32 v4, 0x7fffffff, v6
	v_pk_mul_f32 v[4:5], v[106:107], v[4:5]
	s_nop 0
	v_lshrrev_b32_e32 v8, 18, v5
	v_add_u32_e32 v9, 0xfffff0c0, v8
	v_add_u32_e32 v8, 0xfffff180, v8
	v_ashrrev_i32_e32 v8, 2, v8
	s_nop 0
	s_nop 1
	v_max_i32_e32 v5, v8, v9
	v_med3_i32 v5, v5, 0, v188
	v_or_b32_e32 v8, 0x100, v5
	v_sub_u32_e32 v5, 0xfe, v5
	v_cmp_gt_f32_e32 vcc, 0, v7
	s_nop 1
	v_cndmask_b32_e32 v5, v189, v5, vcc
	v_cmp_lt_f32_e32 vcc, 0, v7
	s_nop 1
	v_cndmask_b32_e32 v5, v5, v8, vcc
	v_lshlrev_b32_e32 v7, 1, v5
	v_and_b32_e32 v7, 0x3fc, v7
	v_lshlrev_b32_e32 v5, 4, v5
	v_add_u32_e32 v7, v136, v7
	v_lshlrev_b32_e64 v5, v5, 1
	ds_add_u32 v7, v5 offset:4096
	v_lshrrev_b32_e32 v5, 18, v4
	v_add_u32_e32 v7, 0xfffff0c0, v5
	v_add_u32_e32 v5, 0xfffff180, v5
	v_ashrrev_i32_e32 v5, 2, v5
	s_nop 0
	s_nop 1
	v_max_i32_e32 v4, v5, v7
	v_med3_i32 v4, v4, 0, v188
	v_or_b32_e32 v5, 0x100, v4
	v_sub_u32_e32 v4, 0xfe, v4
	v_cmp_gt_f32_e32 vcc, 0, v6
	s_nop 1
	v_cndmask_b32_e32 v4, v189, v4, vcc
	v_cmp_lt_f32_e32 vcc, 0, v6
	s_nop 1
	v_cndmask_b32_e32 v4, v4, v5, vcc
	v_lshlrev_b32_e32 v5, 1, v4
	v_and_b32_e32 v5, 0x3fc, v5
	v_lshlrev_b32_e32 v4, 4, v4
	v_add_u32_e32 v5, v136, v5
	v_lshlrev_b32_e64 v4, v4, 1
	ds_add_u32 v5, v4 offset:6144
	s_branch .LBB0_299

; DI unsigned mono_key(float s) {
;   unsigned u = __float_as_uint(s);
;   return (u & 0x80000000u) ? ~u : (u | 0x80000000u);
; }
; DI void attn_item(const Params& P, unsigned char* smem, bool samp, int b, int c) {
;     ...
;           const bool valid = !tail || ((kt * 64 + hf * 32 + l32) < nkeys);
;           for (int i = 0; i < 4; ++i) {
;             const unsigned key = mono_key(sc[i][hf]);
;             bool sel = valid && (key >= khi[i]);
;             const bool inb = valid && (key >= klo[i]) && (key < khi[i]);
;             const bool zb = (bst[i] == 255);
;             if (anyzb) {
;               const unsigned long long bal = __ballot(inb && zb);
;               const unsigned mym = g ? (unsigned)(bal >> 32) : (unsigned)bal;
;               const int rank = __popc(mym & ltmask);
;               sel = sel || (inb && zb && (seen[i] + rank < nd[i]));
.LBB0_620:
	s_nop 9
	v_med3_f32 v20, v20, 0, v187
	v_mul_f32_e32 v20, v52, v20
	v_med3_f32 v21, v21, 0, v187
	v_fmac_f32_e32 v20, v53, v21
	v_med3_f32 v21, v22, 0, v187
	v_fmac_f32_e32 v20, v54, v21
	v_med3_f32 v21, v23, 0, v187
	v_fmac_f32_e32 v20, v55, v21
	s_cmp_le_u32 s21, s1
	v_add_u32_e32 v21, s21, v195
	s_cselect_b64 s[68:69], -1, 0
	v_cmp_gt_u32_e32 vcc, s0, v21
	s_or_b64 s[66:67], s[68:69], vcc
	v_ashrrev_i32_e32 v22, 31, v20
	v_or_b32_e32 v22, 0x80000000, v22
	v_xor_b32_e32 v20, v20, v22
	s_nop 0
	s_nop 0
	v_cmp_ge_u32_e32 vcc, v20, v69
	s_and_b64 s[62:63], s[66:67], vcc
	v_cmp_ge_u32_e32 vcc, v20, v68
	s_and_b64 s[58:59], s[66:67], vcc
	v_cmp_lt_u32_e32 vcc, v20, v69
	v_cndmask_b32_e64 v22, 0, 1, s[88:89]
	s_and_b64 s[64:65], s[58:59], vcc
	v_cmp_ne_u32_e64 s[58:59], 1, v22
	s_andn2_b64 vcc, exec, s[88:89]
	s_cbranch_vccnz .LBB0_622
	s_and_b64 vcc, s[18:19], s[64:65]
	s_mov_b64 s[60:61], vcc
	s_nop 0
	v_cndmask_b32_e64 v126, 0, 1, s[62:63]
	s_nop 0
	v_lshrrev_b64 v[22:23], v114, s[60:61]
	v_and_b32_e32 v23, v22, v109
	v_bcnt_u32_b32 v23, v23, v124
	v_cmp_lt_i32_e64 s[60:61], v23, v121
	v_bcnt_u32_b32 v124, v22, v124
	s_nop 0
	v_cndmask_b32_e64 v23, 0, 1, s[60:61]
	v_cndmask_b32_e32 v23, v126, v23, vcc
	v_and_b32_e32 v23, 1, v23
	v_cmp_eq_u32_e32 vcc, 1, v23
	s_andn2_b64 s[60:61], s[62:63], exec
	s_and_b64 s[62:63], vcc, exec
	s_or_b64 s[62:63], s[60:61], s[62:63]

; DI unsigned mono_key(float s) {
;   unsigned u = __float_as_uint(s);
;   return (u & 0x80000000u) ? ~u : (u | 0x80000000u);
; }
; DI void attn_item(const Params& P, unsigned char* smem, bool samp, int b, int c) {
;     ...
;           for (int i = 0; i < 4; ++i) {
;             const unsigned key = mono_key(sc[i][hf]);
;             bool sel = valid && (key >= khi[i]);
;             const bool inb = valid && (key >= klo[i]) && (key < khi[i]);
;             const bool zb = (bst[i] == 255);
;             if (anyzb) {
;               const unsigned long long bal = __ballot(inb && zb);
;               const unsigned mym = g ? (unsigned)(bal >> 32) : (unsigned)bal;
;               const int rank = __popc(mym & ltmask);
;               sel = sel || (inb && zb && (seen[i] + rank < nd[i]));
;               seen[i] += __popc(mym);
;             }
;             const bool cand = inb && !zb;
;             const unsigned long long cb = __ballot(cand);
;             if (cb != 0ull) {
;               const unsigned mym = g ? (unsigned)(cb >> 32) : (unsigned)cb;
;               const int slot = cbase[i] + __popc(mym & ltmask);
;               if (cand && slot < CAND_CAP)
;                 lst[(g + 2 * i) * CAND_CAP + slot] = make_uint2(key, (unsigned)(kt * 64 + hf * 32 + l32));
;               cbase[i] += __popc(mym);
;             }
.LBB0_626:
	v_med3_f32 v20, v24, 0, v187
	v_mul_f32_e32 v20, v56, v20
	v_med3_f32 v22, v25, 0, v187
	v_fmac_f32_e32 v20, v57, v22
	v_med3_f32 v22, v26, 0, v187
	v_fmac_f32_e32 v20, v58, v22
	v_med3_f32 v22, v27, 0, v187
	v_fmac_f32_e32 v20, v59, v22
	s_mov_b64 s[60:61], s[62:63]
	s_nop 0
	v_ashrrev_i32_e32 v22, 31, v20
	v_or_b32_e32 v22, 0x80000000, v22
	v_xor_b32_e32 v20, v20, v22
	s_nop 0
	s_nop 0
	v_cmp_ge_u32_e32 vcc, v20, v71
	s_and_b64 s[64:65], s[66:67], vcc
	v_cmp_ge_u32_e32 vcc, v20, v70
	s_and_b64 s[70:71], s[66:67], vcc
	v_cmp_lt_u32_e64 s[62:63], v20, v71
	s_and_b64 vcc, exec, s[58:59]
	s_and_b64 s[70:71], s[70:71], s[62:63]
	s_cbranch_vccnz .LBB0_628
	s_and_b64 vcc, s[70:71], s[8:9]
	s_mov_b64 s[62:63], vcc
	s_nop 0
	v_cndmask_b32_e64 v24, 0, 1, s[64:65]
	s_nop 0
	v_lshrrev_b64 v[22:23], v114, s[62:63]
	v_and_b32_e32 v23, v22, v109
	v_bcnt_u32_b32 v23, v23, v122
	v_cmp_lt_i32_e64 s[62:63], v23, v123
	v_bcnt_u32_b32 v122, v22, v122
	s_nop 0
	v_cndmask_b32_e64 v23, 0, 1, s[62:63]
	v_cndmask_b32_e32 v23, v24, v23, vcc
	v_and_b32_e32 v23, 1, v23
	v_cmp_eq_u32_e32 vcc, 1, v23
	s_andn2_b64 s[62:63], s[64:65], exec
	s_and_b64 s[64:65], vcc, exec
	s_or_b64 s[64:65], s[62:63], s[64:65]

; DI unsigned mono_key(float s) {
;   unsigned u = __float_as_uint(s);
;   return (u & 0x80000000u) ? ~u : (u | 0x80000000u);
; }
; DI void attn_item(const Params& P, unsigned char* smem, bool samp, int b, int c) {
;     ...
;           for (int i = 0; i < 4; ++i) {
;             const unsigned key = mono_key(sc[i][hf]);
;             bool sel = valid && (key >= khi[i]);
;             const bool inb = valid && (key >= klo[i]) && (key < khi[i]);
;             const bool zb = (bst[i] == 255);
;             if (anyzb) {
;               const unsigned long long bal = __ballot(inb && zb);
;               const unsigned mym = g ? (unsigned)(bal >> 32) : (unsigned)bal;
;               const int rank = __popc(mym & ltmask);
;               sel = sel || (inb && zb && (seen[i] + rank < nd[i]));
;               seen[i] += __popc(mym);
;             }
;             const bool cand = inb && !zb;
;             const unsigned long long cb = __ballot(cand);
;             if (cb != 0ull) {
;               const unsigned mym = g ? (unsigned)(cb >> 32) : (unsigned)cb;
;               const int slot = cbase[i] + __popc(mym & ltmask);
;               if (cand && slot < CAND_CAP)
;                 lst[(g + 2 * i) * CAND_CAP + slot] = make_uint2(key, (unsigned)(kt * 64 + hf * 32 + l32));
;               cbase[i] += __popc(mym);
;             }
.LBB0_632:
	v_med3_f32 v20, v28, 0, v187
	v_mul_f32_e32 v20, v60, v20
	v_med3_f32 v22, v29, 0, v187
	v_fmac_f32_e32 v20, v61, v22
	v_med3_f32 v22, v30, 0, v187
	v_fmac_f32_e32 v20, v62, v22
	v_med3_f32 v22, v31, 0, v187
	v_fmac_f32_e32 v20, v63, v22
	s_mov_b64 s[62:63], s[64:65]
	s_nop 0
	v_ashrrev_i32_e32 v22, 31, v20
	v_or_b32_e32 v22, 0x80000000, v22
	v_xor_b32_e32 v20, v20, v22
	s_nop 0
	s_nop 0
	v_cmp_ge_u32_e32 vcc, v20, v73
	s_and_b64 s[70:71], s[66:67], vcc
	v_cmp_ge_u32_e32 vcc, v20, v72
	s_and_b64 s[72:73], s[66:67], vcc
	v_cmp_lt_u32_e64 s[64:65], v20, v73
	s_and_b64 vcc, exec, s[58:59]
	s_and_b64 s[72:73], s[72:73], s[64:65]
	s_cbranch_vccnz .LBB0_634
	s_and_b64 vcc, s[72:73], s[12:13]
	s_mov_b64 s[64:65], vcc
	s_nop 0
	v_cndmask_b32_e64 v24, 0, 1, s[70:71]
	s_nop 0
	v_lshrrev_b64 v[22:23], v114, s[64:65]
	v_and_b32_e32 v23, v22, v109
	v_bcnt_u32_b32 v23, v23, v120
	v_cmp_lt_i32_e64 s[64:65], v23, v125
	v_bcnt_u32_b32 v120, v22, v120
	s_nop 0
	v_cndmask_b32_e64 v23, 0, 1, s[64:65]
	v_cndmask_b32_e32 v23, v24, v23, vcc
	v_and_b32_e32 v23, 1, v23
	v_cmp_eq_u32_e32 vcc, 1, v23
	s_andn2_b64 s[64:65], s[70:71], exec
	s_and_b64 s[70:71], vcc, exec
	s_or_b64 s[70:71], s[64:65], s[70:71]

; DI unsigned mono_key(float s) {
;   unsigned u = __float_as_uint(s);
;   return (u & 0x80000000u) ? ~u : (u | 0x80000000u);
; }
; DI void attn_item(const Params& P, unsigned char* smem, bool samp, int b, int c) {
;     ...
;           for (int i = 0; i < 4; ++i) {
;             const unsigned key = mono_key(sc[i][hf]);
;             bool sel = valid && (key >= khi[i]);
;             const bool inb = valid && (key >= klo[i]) && (key < khi[i]);
;             const bool zb = (bst[i] == 255);
;             if (anyzb) {
;               const unsigned long long bal = __ballot(inb && zb);
;               const unsigned mym = g ? (unsigned)(bal >> 32) : (unsigned)bal;
;               const int rank = __popc(mym & ltmask);
;               sel = sel || (inb && zb && (seen[i] + rank < nd[i]));
;               seen[i] += __popc(mym);
;             }
;             const bool cand = inb && !zb;
;             const unsigned long long cb = __ballot(cand);
;             if (cb != 0ull) {
;               const unsigned mym = g ? (unsigned)(cb >> 32) : (unsigned)cb;
;               const int slot = cbase[i] + __popc(mym & ltmask);
;               if (cand && slot < CAND_CAP)
;                 lst[(g + 2 * i) * CAND_CAP + slot] = make_uint2(key, (unsigned)(kt * 64 + hf * 32 + l32));
;               cbase[i] += __popc(mym);
;             }
.LBB0_638:
	v_med3_f32 v20, v32, 0, v187
	v_mul_f32_e32 v20, v64, v20
	v_med3_f32 v22, v33, 0, v187
	v_fmac_f32_e32 v20, v65, v22
	v_med3_f32 v22, v34, 0, v187
	v_fmac_f32_e32 v20, v66, v22
	v_med3_f32 v22, v35, 0, v187
	v_fmac_f32_e32 v20, v67, v22
	s_mov_b64 s[64:65], s[70:71]
	s_nop 0
	v_ashrrev_i32_e32 v22, 31, v20
	v_or_b32_e32 v22, 0x80000000, v22
	v_xor_b32_e32 v20, v20, v22
	s_nop 0
	s_nop 0
	v_cmp_ge_u32_e32 vcc, v20, v75
	s_and_b64 s[70:71], s[66:67], vcc
	v_cmp_ge_u32_e32 vcc, v20, v74
	s_and_b64 s[72:73], s[66:67], vcc
	v_cmp_lt_u32_e64 s[66:67], v20, v75
	s_and_b64 vcc, exec, s[58:59]
	s_and_b64 s[72:73], s[72:73], s[66:67]
	s_cbranch_vccnz .LBB0_640
	s_and_b64 vcc, s[72:73], s[16:17]
	s_mov_b64 s[66:67], vcc
	s_nop 0
	v_cndmask_b32_e64 v24, 0, 1, s[70:71]
	s_nop 0
	v_lshrrev_b64 v[22:23], v114, s[66:67]
	v_and_b32_e32 v23, v22, v109
	v_bcnt_u32_b32 v23, v23, v119
	v_cmp_lt_i32_e64 s[66:67], v23, v127
	v_bcnt_u32_b32 v119, v22, v119
	s_nop 0
	v_cndmask_b32_e64 v23, 0, 1, s[66:67]
	v_cndmask_b32_e32 v23, v24, v23, vcc
	v_and_b32_e32 v23, 1, v23
	v_cmp_eq_u32_e32 vcc, 1, v23
	s_andn2_b64 s[66:67], s[70:71], exec
	s_and_b64 s[70:71], vcc, exec
	s_or_b64 s[70:71], s[66:67], s[70:71]

; DI unsigned mono_key(float s) {
;   unsigned u = __float_as_uint(s);
;   return (u & 0x80000000u) ? ~u : (u | 0x80000000u);
; }
; DI void attn_item(const Params& P, unsigned char* smem, bool samp, int b, int c) {
;     ...
;           for (int i = 0; i < 4; ++i) {
;             const unsigned key = mono_key(sc[i][hf]);
;             bool sel = valid && (key >= khi[i]);
;             const bool inb = valid && (key >= klo[i]) && (key < khi[i]);
;             const bool zb = (bst[i] == 255);
;             if (anyzb) {
;               const unsigned long long bal = __ballot(inb && zb);
;               const unsigned mym = g ? (unsigned)(bal >> 32) : (unsigned)bal;
;               const int rank = __popc(mym & ltmask);
;               sel = sel || (inb && zb && (seen[i] + rank < nd[i]));
;               seen[i] += __popc(mym);
;             }
;             const bool cand = inb && !zb;
;             const unsigned long long cb = __ballot(cand);
;             if (cb != 0ull) {
;               const unsigned mym = g ? (unsigned)(cb >> 32) : (unsigned)cb;
;               const int slot = cbase[i] + __popc(mym & ltmask);
;               if (cand && slot < CAND_CAP)
;                 lst[(g + 2 * i) * CAND_CAP + slot] = make_uint2(key, (unsigned)(kt * 64 + hf * 32 + l32));
;               cbase[i] += __popc(mym);
;             }
.LBB0_644:
	v_med3_f32 v4, v4, 0, v187
	v_mul_f32_e32 v4, v52, v4
	v_med3_f32 v5, v5, 0, v187
	v_fmac_f32_e32 v4, v53, v5
	v_med3_f32 v5, v6, 0, v187
	v_fmac_f32_e32 v4, v54, v5
	v_med3_f32 v5, v7, 0, v187
	v_fmac_f32_e32 v4, v55, v5
	s_mov_b64 s[66:67], s[70:71]
	s_nop 0
	v_add_u32_e32 v5, 32, v21
	v_cmp_gt_u32_e32 vcc, s0, v5
	s_or_b64 s[74:75], s[68:69], vcc
	v_ashrrev_i32_e32 v6, 31, v4
	v_or_b32_e32 v6, 0x80000000, v6
	v_xor_b32_e32 v4, v4, v6
	s_nop 0
	s_nop 0
	v_cmp_ge_u32_e32 vcc, v4, v69
	s_and_b64 s[70:71], s[74:75], vcc
	v_cmp_ge_u32_e32 vcc, v4, v68
	s_and_b64 s[72:73], s[74:75], vcc
	v_cmp_lt_u32_e64 s[68:69], v4, v69
	s_and_b64 vcc, exec, s[58:59]
	s_and_b64 s[72:73], s[72:73], s[68:69]
	s_cbranch_vccnz .LBB0_646
	s_and_b64 vcc, s[18:19], s[72:73]
	s_mov_b64 s[68:69], vcc
	s_nop 0
	v_cndmask_b32_e64 v20, 0, 1, s[70:71]
	s_nop 0
	v_lshrrev_b64 v[6:7], v114, s[68:69]
	v_and_b32_e32 v7, v6, v109
	v_bcnt_u32_b32 v7, v7, v124
	v_cmp_lt_i32_e64 s[68:69], v7, v121
	v_bcnt_u32_b32 v124, v6, v124
	s_nop 0
	v_cndmask_b32_e64 v7, 0, 1, s[68:69]
	v_cndmask_b32_e32 v7, v20, v7, vcc
	v_and_b32_e32 v7, 1, v7
	v_cmp_eq_u32_e32 vcc, 1, v7
	s_andn2_b64 s[68:69], s[70:71], exec
	s_and_b64 s[70:71], vcc, exec
	s_or_b64 s[70:71], s[68:69], s[70:71]

; DI unsigned mono_key(float s) {
;   unsigned u = __float_as_uint(s);
;   return (u & 0x80000000u) ? ~u : (u | 0x80000000u);
; }
; DI void attn_item(const Params& P, unsigned char* smem, bool samp, int b, int c) {
;     ...
;           for (int i = 0; i < 4; ++i) {
;             const unsigned key = mono_key(sc[i][hf]);
;             bool sel = valid && (key >= khi[i]);
;             const bool inb = valid && (key >= klo[i]) && (key < khi[i]);
;             const bool zb = (bst[i] == 255);
;             if (anyzb) {
;               const unsigned long long bal = __ballot(inb && zb);
;               const unsigned mym = g ? (unsigned)(bal >> 32) : (unsigned)bal;
;               const int rank = __popc(mym & ltmask);
;               sel = sel || (inb && zb && (seen[i] + rank < nd[i]));
;               seen[i] += __popc(mym);
;             }
;             const bool cand = inb && !zb;
;             const unsigned long long cb = __ballot(cand);
;             if (cb != 0ull) {
;               const unsigned mym = g ? (unsigned)(cb >> 32) : (unsigned)cb;
;               const int slot = cbase[i] + __popc(mym & ltmask);
;               if (cand && slot < CAND_CAP)
;                 lst[(g + 2 * i) * CAND_CAP + slot] = make_uint2(key, (unsigned)(kt * 64 + hf * 32 + l32));
;               cbase[i] += __popc(mym);
;             }
.LBB0_650:
	v_med3_f32 v4, v8, 0, v187
	v_mul_f32_e32 v4, v56, v4
	v_med3_f32 v6, v9, 0, v187
	v_fmac_f32_e32 v4, v57, v6
	v_med3_f32 v6, v10, 0, v187
	v_fmac_f32_e32 v4, v58, v6
	v_med3_f32 v6, v11, 0, v187
	v_fmac_f32_e32 v4, v59, v6
	s_mov_b64 s[68:69], s[70:71]
	s_nop 0
	v_ashrrev_i32_e32 v6, 31, v4
	v_or_b32_e32 v6, 0x80000000, v6
	v_xor_b32_e32 v4, v4, v6
	s_nop 0
	s_nop 0
	v_cmp_ge_u32_e32 vcc, v4, v71
	s_and_b64 s[72:73], s[74:75], vcc
	v_cmp_ge_u32_e32 vcc, v4, v70
	s_and_b64 s[76:77], s[74:75], vcc
	v_cmp_lt_u32_e64 s[70:71], v4, v71
	s_and_b64 vcc, exec, s[58:59]
	s_and_b64 s[78:79], s[76:77], s[70:71]
	s_cbranch_vccnz .LBB0_652
	s_and_b64 vcc, s[78:79], s[8:9]
	s_mov_b64 s[70:71], vcc
	s_nop 0
	v_cndmask_b32_e64 v8, 0, 1, s[72:73]
	s_nop 0
	v_lshrrev_b64 v[6:7], v114, s[70:71]
	v_and_b32_e32 v7, v6, v109
	v_bcnt_u32_b32 v7, v7, v122
	v_cmp_lt_i32_e64 s[70:71], v7, v123
	v_bcnt_u32_b32 v122, v6, v122
	s_nop 0
	v_cndmask_b32_e64 v7, 0, 1, s[70:71]
	v_cndmask_b32_e32 v7, v8, v7, vcc
	v_and_b32_e32 v7, 1, v7
	v_cmp_eq_u32_e32 vcc, 1, v7
	s_andn2_b64 s[70:71], s[72:73], exec
	s_and_b64 s[72:73], vcc, exec
	s_or_b64 s[72:73], s[70:71], s[72:73]

; DI unsigned mono_key(float s) {
;   unsigned u = __float_as_uint(s);
;   return (u & 0x80000000u) ? ~u : (u | 0x80000000u);
; }
; DI void attn_item(const Params& P, unsigned char* smem, bool samp, int b, int c) {
;     ...
;           for (int i = 0; i < 4; ++i) {
;             const unsigned key = mono_key(sc[i][hf]);
;             bool sel = valid && (key >= khi[i]);
;             const bool inb = valid && (key >= klo[i]) && (key < khi[i]);
;             const bool zb = (bst[i] == 255);
;             if (anyzb) {
;               const unsigned long long bal = __ballot(inb && zb);
;               const unsigned mym = g ? (unsigned)(bal >> 32) : (unsigned)bal;
;               const int rank = __popc(mym & ltmask);
;               sel = sel || (inb && zb && (seen[i] + rank < nd[i]));
;               seen[i] += __popc(mym);
;             }
;             const bool cand = inb && !zb;
;             const unsigned long long cb = __ballot(cand);
;             if (cb != 0ull) {
;               const unsigned mym = g ? (unsigned)(cb >> 32) : (unsigned)cb;
;               const int slot = cbase[i] + __popc(mym & ltmask);
;               if (cand && slot < CAND_CAP)
;                 lst[(g + 2 * i) * CAND_CAP + slot] = make_uint2(key, (unsigned)(kt * 64 + hf * 32 + l32));
;               cbase[i] += __popc(mym);
;             }
.LBB0_656:
	v_med3_f32 v4, v12, 0, v187
	v_mul_f32_e32 v4, v60, v4
	v_med3_f32 v6, v13, 0, v187
	v_fmac_f32_e32 v4, v61, v6
	v_med3_f32 v6, v14, 0, v187
	v_fmac_f32_e32 v4, v62, v6
	v_med3_f32 v6, v15, 0, v187
	v_fmac_f32_e32 v4, v63, v6
	s_mov_b64 s[70:71], s[72:73]
	s_nop 0
	v_ashrrev_i32_e32 v6, 31, v4
	v_or_b32_e32 v6, 0x80000000, v6
	v_xor_b32_e32 v4, v4, v6
	s_nop 0
	s_nop 0
	v_cmp_ge_u32_e32 vcc, v4, v73
	s_and_b64 s[78:79], s[74:75], vcc
	v_cmp_ge_u32_e32 vcc, v4, v72
	s_and_b64 s[76:77], s[74:75], vcc
	v_cmp_lt_u32_e64 s[72:73], v4, v73
	s_and_b64 vcc, exec, s[58:59]
	s_and_b64 s[76:77], s[76:77], s[72:73]
	s_cbranch_vccnz .LBB0_658
	s_and_b64 vcc, s[76:77], s[12:13]
	s_mov_b64 s[72:73], vcc
	s_nop 0
	v_cndmask_b32_e64 v8, 0, 1, s[78:79]
	s_nop 0
	v_lshrrev_b64 v[6:7], v114, s[72:73]
	v_and_b32_e32 v7, v6, v109
	v_bcnt_u32_b32 v7, v7, v120
	v_cmp_lt_i32_e64 s[72:73], v7, v125
	v_bcnt_u32_b32 v120, v6, v120
	s_nop 0
	v_cndmask_b32_e64 v7, 0, 1, s[72:73]
	v_cndmask_b32_e32 v7, v8, v7, vcc
	v_and_b32_e32 v7, 1, v7
	v_cmp_eq_u32_e32 vcc, 1, v7
	s_andn2_b64 s[72:73], s[78:79], exec
	s_and_b64 s[78:79], vcc, exec
	s_or_b64 s[78:79], s[72:73], s[78:79]

; DI unsigned mono_key(float s) {
;   unsigned u = __float_as_uint(s);
;   return (u & 0x80000000u) ? ~u : (u | 0x80000000u);
; }
; DI void attn_item(const Params& P, unsigned char* smem, bool samp, int b, int c) {
;     ...
;           for (int i = 0; i < 4; ++i) {
;             const unsigned key = mono_key(sc[i][hf]);
;             bool sel = valid && (key >= khi[i]);
;             const bool inb = valid && (key >= klo[i]) && (key < khi[i]);
;             const bool zb = (bst[i] == 255);
;             if (anyzb) {
;               const unsigned long long bal = __ballot(inb && zb);
;               const unsigned mym = g ? (unsigned)(bal >> 32) : (unsigned)bal;
;               const int rank = __popc(mym & ltmask);
;               sel = sel || (inb && zb && (seen[i] + rank < nd[i]));
;               seen[i] += __popc(mym);
;             }
;             const bool cand = inb && !zb;
;             const unsigned long long cb = __ballot(cand);
;             if (cb != 0ull) {
;               const unsigned mym = g ? (unsigned)(cb >> 32) : (unsigned)cb;
;               const int slot = cbase[i] + __popc(mym & ltmask);
;               if (cand && slot < CAND_CAP)
;                 lst[(g + 2 * i) * CAND_CAP + slot] = make_uint2(key, (unsigned)(kt * 64 + hf * 32 + l32));
;               cbase[i] += __popc(mym);
;             }
.LBB0_662:
	v_med3_f32 v4, v16, 0, v187
	v_mul_f32_e32 v4, v64, v4
	v_med3_f32 v6, v17, 0, v187
	v_fmac_f32_e32 v4, v65, v6
	v_med3_f32 v6, v18, 0, v187
	v_fmac_f32_e32 v4, v66, v6
	v_med3_f32 v6, v19, 0, v187
	v_fmac_f32_e32 v4, v67, v6
	s_mov_b64 s[72:73], s[78:79]
	s_nop 0
	v_ashrrev_i32_e32 v6, 31, v4
	v_or_b32_e32 v6, 0x80000000, v6
	v_xor_b32_e32 v4, v4, v6
	s_nop 0
	s_nop 0
	v_cmp_ge_u32_e32 vcc, v4, v75
	s_and_b64 s[78:79], s[74:75], vcc
	v_cmp_ge_u32_e32 vcc, v4, v74
	s_and_b64 s[76:77], s[74:75], vcc
	v_cmp_lt_u32_e64 s[74:75], v4, v75
	s_and_b64 vcc, exec, s[58:59]
	s_and_b64 s[74:75], s[76:77], s[74:75]
	s_cbranch_vccnz .LBB0_664
	s_and_b64 vcc, s[74:75], s[16:17]
	s_mov_b64 s[58:59], vcc
	s_nop 0
	v_cndmask_b32_e64 v8, 0, 1, s[78:79]
	s_nop 0
	v_lshrrev_b64 v[6:7], v114, s[58:59]
	v_and_b32_e32 v7, v6, v109
	v_bcnt_u32_b32 v7, v7, v119
	v_cmp_lt_i32_e64 s[58:59], v7, v127
	v_bcnt_u32_b32 v119, v6, v119
	s_nop 0
	v_cndmask_b32_e64 v7, 0, 1, s[58:59]
	v_cndmask_b32_e32 v7, v8, v7, vcc
	v_and_b32_e32 v7, 1, v7
	v_cmp_eq_u32_e32 vcc, 1, v7
	s_andn2_b64 s[58:59], s[78:79], exec
	s_and_b64 s[76:77], vcc, exec
	s_or_b64 s[78:79], s[58:59], s[76:77]
